# conv-branch items: thread-to-item map changed so the partial third pass runs on a quarter of every workgroup instead of all of the first 64
# baseline (speedup 1.0000x reference)
.LBB0_327:
	s_or_b64 exec, exec, s[4:5]
	v_mov_b32_e32 v126, v164
	s_waitcnt lgkmcnt(0)
	s_barrier
	s_add_u32 s14, s34, 0xc000000
	v_lshrrev_b32_e32 v154, 7, v126
	v_mul_u32_u24_e32 v154, s26, v154
	v_add_u32_e32 v154, s2, v154
	v_and_b32_e32 v155, 0x7f, v126
	v_lshl_add_u32 v94, v154, 7, v155
	s_mov_b32 s3, 0x48000
	s_addc_u32 s15, s35, 0
	s_mov_b32 s6, 12
	s_mov_b32 s4, 2
	v_cmp_gt_i32_e32 vcc, s3, v94
	v_lshlrev_b32_e32 v127, 3, v126
	s_and_saveexec_b64 s[8:9], vcc
	s_cbranch_execz .LBB0_340
	s_ashr_i32 s7, s6, 31
	s_lshl_b64 s[6:7], s[6:7], 3
	s_add_u32 s6, s0, s6
	s_addc_u32 s7, s1, s7
	s_ashr_i32 s5, s4, 31
	s_lshl_b64 s[4:5], s[4:5], 3
	s_add_u32 s4, s0, s4
	s_addc_u32 s5, s1, s5
	s_load_dwordx2 s[10:11], s[6:7], 0x0
	s_load_dwordx2 s[38:39], s[4:5], 0x0
	s_lshl_b32 s3, s26, 9
	v_lshlrev_b32_e32 v95, 3, v94
	s_lshl_b32 s19, s26, 12
	s_mov_b64 s[40:41], 0
	s_movk_i32 s25, 0x1fff
	s_movk_i32 s29, 0x2000
	v_mov_b32_e32 v96, 0x7fc
	v_mov_b32_e32 v49, 0
	s_movk_i32 s48, 0x4800
	s_movk_i32 s49, 0x1000
	s_mov_b64 s[42:43], 0x1000
	s_mov_b64 s[44:45], 0x2000
	s_mov_b32 s50, 0x17200000
	s_mov_b32 s51, 0x47fff
	v_mov_b32_e32 v97, 0x5808000
	v_mov_b32_e32 v98, 0x5800000
	s_branch .LBB0_330
